# v20 with the attention steady-loop head moved to 8 mod 64 (all later code placement as v20)
# baseline (speedup 1.0000x reference)
; #define WAIT_BAR(N) asm volatile("s_waitcnt vmcnt(" #N ") lgkmcnt(0)\n\ts_barrier":::"memory")
;   #define DMA_K(t,slot) glds16(ksrc+(long)(t)*KVBLK*DM,(unsigned)__builtin_amdgcn_readfirstlane(kdst+(slot)))
;   #define DMA_V(t,slot) do{ glds16(vsrc+(long)(t)*KVBLK*DM,(unsigned)__builtin_amdgcn_readfirstlane(vdst+(slot))); glds16(vsrc+64+(long)(t)*KVBLK*DM,(unsigned)__builtin_amdgcn_readfirstlane(vdst2+(slot))); }while(0)
;   #define CMASK(P0,P1,t) do{int jb_=(t)-(NT-4); if(jb_>=0)cmask(P0,P1,jb_,qrel,hi);}while(0)
;   #define START(P0,P1) do{ resc=false; \
;     { _Pragma("unroll") for(int r=0;r<16;++r){P0[r]=fsub_s(P0[r],mhat);P1[r]=fsub_s(P1[r],mhat);} \
;       } \
;     _Pragma("unroll") for(int r=0;r<16;++r)P0[r]=__builtin_amdgcn_exp2f(P0[r]); }while(0)
;   #define ROT() do{sl_prev=sl_cur;sl_cur=sl_next;sl_next=(sl_next==(NSLOT-1)*SLOTB)?0:sl_next+SLOTB;}while(0)
;   #define CMASK(P0,P1,t) do{}while(0)
;   #define CMASK(P0,P1,t) do{int jb_=(t)-(NT-4); if(jb_>=0)cmask(P0,P1,jb_,qrel,hi);}while(0)
; template<int THRL> __device__ __forceinline__ void attn_unit(int b,int h,int qb,unsigned char*wsb,char*shm,float kmax,const int CMB,float lam){
;     ...
;   const float mhat=sqrtf(q2_)*kmax*1.004f+0.02f;
;   float l_reg=0.f;f32x16 o[2];o[0]=f32x16{};o[1]=f32x16{};f32x16 o2[2];o2[0]=f32x16{};o2[1]=f32x16{};const f32x16 negm=f32x16{};
;   const int qrel=wid*QBLK+r32;
;     ...
;   bool resc=false;
;     ...
;   f32x16 pA0,pA1,pB0,pB1;
;   int sl_prev=0,sl_cur=0,sl_next=SLOTB;
;     ...
;   DMA_K(2,2*SLOTB);
;   WAIT_BAR(4);
;   qkt(pA0,pA1,Kbase,qr,negm,r32,hi);asm volatile("s_nop 15\n\ts_nop 7":"+v"(pA0),"+v"(pA1));CMASK(pA0,pA1,0);
;   START(pA0,pA1);
;   _Pragma("unroll") for(int r=0;r<16;++r)pA1[r]=__builtin_amdgcn_exp2f(pA1[r]);
;   WAIT_BAR(0);
;   DMA_K(3,0);DMA_V(1,SLOTB);
;   ROT();
;   kload8(kf,kp0+sl_cur);
;   WAIT_BAR(3);
; __global__ void __launch_bounds__(NTHR, 2) fwd_megakernel(Args args_unused) {
;     ...
;                     const float kmax = 1.01f * sqrtf(__uint_as_float(__builtin_amdgcn_readfirstlane(__hip_atomic_load((unsigned*)(ws + WS_KMAX) + 2 * bh, __ATOMIC_RELAXED, __HIP_MEMORY_SCOPE_AGENT)))
;                                                    + __uint_as_float(__builtin_amdgcn_readfirstlane(__hip_atomic_load((unsigned*)(ws + WS_KMAX) + 2 * bh + 1, __ATOMIC_RELAXED, __HIP_MEMORY_SCOPE_AGENT))));
.LBB0_309:
	v_mov_b32_e32 v39, s6
	v_add_f32_e32 v39, s5, v39
	v_mul_f32_e32 v40, 0x4f800000, v39
	v_cmp_gt_f32_e32 vcc, s74, v39
	v_add_f32_e32 v37, v37, v38
	v_mul_f32_e32 v38, 0x4f800000, v37
	v_cndmask_b32_e32 v39, v39, v40, vcc
	v_sqrt_f32_e32 v40, v39
	s_waitcnt vmcnt(0) lgkmcnt(0)
	s_barrier
	s_cmp_lg_u32 0, -1
	s_mov_b32 s37, 0
	v_add_u32_e32 v41, -1, v40
	v_fma_f32 v42, -v41, v40, v39
	v_cmp_ge_f32_e64 s[4:5], 0, v42
	v_add_u32_e32 v42, 1, v40
	s_mov_b32 s6, 1
	v_cndmask_b32_e64 v41, v40, v41, s[4:5]
	v_fma_f32 v40, -v42, v40, v39
	v_cmp_lt_f32_e64 s[4:5], 0, v40
	s_nop 1
	v_cndmask_b32_e64 v40, v41, v42, s[4:5]
	v_mul_f32_e32 v41, 0x37800000, v40
	v_cndmask_b32_e32 v40, v40, v41, vcc
	v_cmp_class_f32_e32 vcc, v39, v237
	s_nop 1
	v_cndmask_b32_e32 v39, v40, v39, vcc
	v_cmp_gt_f32_e32 vcc, s74, v37
	v_lshlrev_b32_e32 v40, 1, v36
	v_and_b32_e32 v251, 32, v40
	v_cndmask_b32_e32 v37, v37, v38, vcc
	v_sqrt_f32_e32 v38, v37
	v_lshlrev_b32_e32 v40, 4, v36
	v_and_b32_e32 v40, 0xc0, v40
	v_lshl_or_b32 v246, v242, 8, v40
	v_add_u32_e32 v40, 0, v251
	v_add3_u32 v252, v40, v249, v246
	v_add_u32_e32 v40, -1, v38
	v_fma_f32 v41, -v40, v38, v37
	v_cmp_ge_f32_e64 s[4:5], 0, v41
	v_add_u32_e32 v41, 1, v38
	v_mul_f32_e32 v39, 0x3f8147ae, v39
	v_cndmask_b32_e64 v40, v38, v40, s[4:5]
	v_fma_f32 v38, -v41, v38, v37
	v_cmp_lt_f32_e64 s[4:5], 0, v38
	s_nop 1
	v_cndmask_b32_e64 v38, v40, v41, s[4:5]
	v_mul_f32_e32 v40, 0x37800000, v38
	v_cndmask_b32_e32 v38, v38, v40, vcc
	v_cmp_class_f32_e32 vcc, v37, v237
	s_mov_b64 s[4:5], 0x60000
	s_nop 0
	v_cndmask_b32_e32 v37, v38, v37, vcc
	v_mul_f32_e32 v37, v39, v37
	v_fmamk_f32 v247, v37, 0x3f808312, v238
	v_sub_f32_e32 v0, v0, v247
	v_sub_f32_e32 v1, v1, v247
	v_sub_f32_e32 v16, v16, v247
	v_sub_f32_e32 v17, v17, v247
	v_sub_f32_e32 v2, v2, v247
	v_sub_f32_e32 v18, v18, v247
	s_nop 0
	v_exp_f32_e32 v96, v0
	v_exp_f32_e32 v97, v1
	v_lshl_add_u64 v[0:1], v[32:33], 0, s[4:5]
	s_mov_b32 s4, m0
	s_mov_b32 m0, s3
	s_nop 0
	global_load_lds_dwordx4 v[0:1], off
	s_mov_b32 m0, s4
	s_mov_b64 s[4:5], 0x20000
	v_lshl_add_u64 v[0:1], v[34:35], 0, s[4:5]
	s_cselect_b32 s4, 0, 0
	s_add_i32 s1, s4, s1
	s_add_i32 s4, s1, 0x8000
	s_mov_b32 s5, m0
	s_mov_b32 m0, s4
	s_nop 0
	global_load_lds_dwordx4 v[0:1], off
	s_mov_b32 m0, s5
	s_mov_b64 s[4:5], 0x20080
	v_lshl_add_u64 v[0:1], v[34:35], 0, s[4:5]
	s_add_i32 s1, s1, 0xe000
	s_mov_b32 s4, m0
	s_mov_b32 m0, s1
	s_nop 0
	global_load_lds_dwordx4 v[0:1], off
	s_mov_b32 m0, s4
	ds_read_b128 v[204:207], v250 offset:8192
	ds_read_b128 v[200:203], v250 offset:8704
	ds_read_b128 v[196:199], v250 offset:10240
	ds_read_b128 v[192:195], v250 offset:10752
	ds_read_b128 v[188:191], v250 offset:12288
	ds_read_b128 v[184:187], v250 offset:12800
	ds_read_b128 v[180:183], v250 offset:14336
	ds_read_b128 v[176:179], v250 offset:14848
	v_sub_f32_e32 v3, v3, v247
	v_sub_f32_e32 v19, v19, v247
	v_sub_f32_e32 v4, v4, v247
	v_sub_f32_e32 v20, v20, v247
	v_sub_f32_e32 v5, v5, v247
	v_sub_f32_e32 v21, v21, v247
	v_sub_f32_e32 v6, v6, v247
	v_sub_f32_e32 v22, v22, v247
	v_sub_f32_e32 v7, v7, v247
	v_sub_f32_e32 v23, v23, v247
	v_sub_f32_e32 v8, v8, v247
	v_sub_f32_e32 v24, v24, v247
	v_sub_f32_e32 v9, v9, v247
	v_sub_f32_e32 v25, v25, v247
	v_sub_f32_e32 v10, v10, v247
	v_sub_f32_e32 v26, v26, v247
	v_sub_f32_e32 v11, v11, v247
	v_sub_f32_e32 v27, v27, v247
	v_sub_f32_e32 v12, v12, v247
	v_sub_f32_e32 v28, v28, v247
	v_sub_f32_e32 v13, v13, v247
	v_sub_f32_e32 v29, v29, v247
	v_sub_f32_e32 v14, v14, v247
	v_sub_f32_e32 v30, v30, v247
	v_sub_f32_e32 v15, v15, v247
	v_sub_f32_e32 v31, v31, v247
	v_exp_f32_e32 v98, v2
	v_exp_f32_e32 v99, v3
	v_exp_f32_e32 v100, v4
	v_exp_f32_e32 v101, v5
	v_exp_f32_e32 v102, v6
	v_exp_f32_e32 v103, v7
	v_exp_f32_e32 v104, v8
	v_exp_f32_e32 v105, v9
	v_exp_f32_e32 v106, v10
	v_exp_f32_e32 v107, v11
	v_exp_f32_e32 v108, v12
	v_exp_f32_e32 v109, v13
	v_exp_f32_e32 v110, v14
	v_exp_f32_e32 v111, v15
	v_exp_f32_e32 v80, v16
	v_exp_f32_e32 v81, v17
	v_exp_f32_e32 v82, v18
	v_exp_f32_e32 v83, v19
	v_exp_f32_e32 v84, v20
	v_exp_f32_e32 v85, v21
	v_exp_f32_e32 v86, v22
	v_exp_f32_e32 v87, v23
	v_exp_f32_e32 v88, v24
	v_exp_f32_e32 v89, v25
	v_exp_f32_e32 v90, v26
	v_exp_f32_e32 v91, v27
	v_exp_f32_e32 v92, v28
	v_exp_f32_e32 v93, v29
	v_exp_f32_e32 v94, v30
	v_exp_f32_e32 v95, v31
	s_waitcnt vmcnt(3) lgkmcnt(0)
	s_barrier
	v_and_b32_e32 v0, 3, v36
	s_andn2_b64 vcc, exec, s[54:55]
	v_lshlrev_b32_e32 v208, 4, v0
	s_cbranch_vccnz .LBB0_313
; template<int THRL> __device__ __forceinline__ void attn_unit(int b,int h,int qb,unsigned char*wsb,char*shm,float kmax,const int CMB,float lam){
;     ...
;   float l_reg=0.f;f32x16 o[2];o[0]=f32x16{};o[1]=f32x16{};f32x16 o2[2];o2[0]=f32x16{};o2[1]=f32x16{};const f32x16 negm=f32x16{};
;   const int qrel=wid*QBLK+r32;
;     ...
;   bool resc=false;
;     ...
;   f32x16 pA0,pA1,pB0,pB1;
;   int sl_prev=0,sl_cur=0,sl_next=SLOTB;
	s_lshl_b32 s1, s43, 6
	s_add_i32 s6, s79, s1
	s_lshr_b32 s4, s6, 7
	s_mov_b32 s5, s7
	s_lshl_b64 s[4:5], s[4:5], 8
	s_lshl_b64 s[36:37], s[68:69], 1
	s_add_u32 s4, s36, s4
	v_mov_b32_e32 v209, v221
	s_addc_u32 s5, s37, s5
	s_lshl_b32 s1, s95, 9
	v_lshl_add_u64 v[0:1], s[4:5], 0, v[208:209]
	s_and_b32 s1, s1, 0x18000
	s_lshl_b64 s[4:5], s[66:67], 1
	s_lshl_b64 s[36:37], s[6:7], 1
	v_lshl_or_b32 v2, v214, 11, s1
	s_add_u32 s1, s64, s36
	s_addc_u32 s6, s65, s37
	v_mov_b32_e32 v3, v221
	s_add_u32 s4, s1, s4
	v_lshl_add_u64 v[0:1], v[0:1], 0, v[2:3]
	s_addc_u32 s5, s6, s5
	v_mov_b32_e32 v64, 0
	s_mov_b32 s33, 6
	v_lshl_add_u64 v[210:211], s[64:65], 0, v[0:1]
	v_lshl_add_u64 v[212:213], s[4:5], 0, v[220:221]
	s_movk_i32 s36, 0x4000
	s_movk_i32 s42, 0x2000
	s_mov_b32 s5, 0
	v_mov_b32_e32 v0, 0
	v_mov_b32_e32 v1, v64
	v_mov_b32_e32 v2, v64
	v_mov_b32_e32 v3, v64
	v_mov_b32_e32 v4, v64
	v_mov_b32_e32 v5, v64
	v_mov_b32_e32 v6, v64
	v_mov_b32_e32 v7, v64
	v_mov_b32_e32 v8, v64
	v_mov_b32_e32 v9, v64
	v_mov_b32_e32 v10, v64
	v_mov_b32_e32 v11, v64
	v_mov_b32_e32 v12, v64
	v_mov_b32_e32 v13, v64
	v_mov_b32_e32 v14, v64
	v_mov_b32_e32 v15, v64
	v_mov_b32_e32 v16, 0
	v_mov_b32_e32 v17, v64
	v_mov_b32_e32 v18, v64
	v_mov_b32_e32 v19, v64
	v_mov_b32_e32 v20, v64
	v_mov_b32_e32 v21, v64
	v_mov_b32_e32 v22, v64
	v_mov_b32_e32 v23, v64
	v_mov_b32_e32 v24, v64
	v_mov_b32_e32 v25, v64
	v_mov_b32_e32 v26, v64
	v_mov_b32_e32 v27, v64
	v_mov_b32_e32 v28, v64
	v_mov_b32_e32 v29, v64
	v_mov_b32_e32 v30, v64
	v_mov_b32_e32 v31, v64
	v_mov_b32_e32 v32, 0
	v_mov_b32_e32 v33, v64
	v_mov_b32_e32 v34, v64
	v_mov_b32_e32 v35, v64
	v_mov_b32_e32 v36, v64
	v_mov_b32_e32 v37, v64
	v_mov_b32_e32 v38, v64
	v_mov_b32_e32 v39, v64
	v_mov_b32_e32 v40, v64
	v_mov_b32_e32 v41, v64
	v_mov_b32_e32 v42, v64
	v_mov_b32_e32 v43, v64
	v_mov_b32_e32 v44, v64
	v_mov_b32_e32 v45, v64
	v_mov_b32_e32 v46, v64
	v_mov_b32_e32 v47, v64
	v_mov_b32_e32 v48, 0
	v_mov_b32_e32 v49, v64
	v_mov_b32_e32 v50, v64
	v_mov_b32_e32 v51, v64
	v_mov_b32_e32 v52, v64
	v_mov_b32_e32 v53, v64
	v_mov_b32_e32 v54, v64
	v_mov_b32_e32 v55, v64
	v_mov_b32_e32 v56, v64
	v_mov_b32_e32 v57, v64
	v_mov_b32_e32 v58, v64
	v_mov_b32_e32 v59, v64
	v_mov_b32_e32 v60, v64
	v_mov_b32_e32 v61, v64
	v_mov_b32_e32 v62, v64
	v_mov_b32_e32 v63, v64
	v_lshlrev_b32_e32 v143, 2, v230
	v_add_u32_e32 v143, 0x12800, v143
	ds_write_b32 v143, v246 offset:32768
	ds_write_b32 v143, v230
	ds_write_b32 v143, v231 offset:2048
	ds_write_b32 v143, v232 offset:4096
	ds_write_b32 v143, v233 offset:6144
	ds_write_b32 v143, v234 offset:8192
	ds_write_b32 v143, v235 offset:10240
	ds_write_b32 v143, v236 offset:12288
	ds_write_b32 v143, v237 offset:14336
	ds_write_b32 v143, v238 offset:16384
	ds_write_b32 v143, v239 offset:18432
	ds_write_b32 v143, v240 offset:20480
	ds_write_b32 v143, v241 offset:22528
	ds_write_b32 v143, v242 offset:24576
	ds_write_b32 v143, v243 offset:26624
	ds_write_b32 v143, v244 offset:28672
	ds_write_b32 v143, v245 offset:30720
	v_mov_b32_e32 v246, v143
	v_xor_b32_e32 v230, 0x80000000, v247
	v_mov_b32_e32 v231, v230
	v_mov_b32_e32 v232, v230
	v_mov_b32_e32 v233, v230
	v_mov_b32_e32 v234, v230
	v_mov_b32_e32 v235, v230
	v_mov_b32_e32 v236, v230
	v_mov_b32_e32 v237, v230
	v_mov_b32_e32 v238, v230
	v_mov_b32_e32 v239, v230
	v_mov_b32_e32 v240, v230
	v_mov_b32_e32 v241, v230
	v_mov_b32_e32 v242, v230
	v_mov_b32_e32 v243, v230
	v_mov_b32_e32 v244, v230
	v_mov_b32_e32 v245, v230
	s_waitcnt lgkmcnt(0)
	s_nop 0
	s_nop 0
	s_nop 0
	s_nop 0
	s_nop 0
	s_nop 0
	s_nop 0
	s_nop 0
.LBB0_311:
	s_mov_b32 s37, s36
	s_mov_b32 s4, s33
	s_mov_b32 s1, s42
	v_add_u32_e32 v209, s5, v252
	ds_read_b64_tr_b16 v[216:217], v209 offset:24576
	ds_read_b64_tr_b16 v[218:219], v209 offset:25088
	v_add_f32_e32 v65, v96, v97
	v_add_f32_e32 v65, v98, v65
	v_add_f32_e32 v65, v99, v65
	v_add_f32_e32 v65, v100, v65
	v_add_f32_e32 v65, v101, v65
	v_cvt_pk_bf16_f32 v172, v96, v97
	v_cvt_pk_bf16_f32 v173, v98, v99
	s_waitcnt lgkmcnt(9)
	v_mfma_f32_32x32x16_bf16 v[128:143], v[204:207], v[156:159], v[230:245]
	ds_read_b64_tr_b16 v[204:205], v209 offset:28672
	ds_read_b64_tr_b16 v[206:207], v209 offset:29184
	v_add_f32_e32 v65, v102, v65
	v_add_f32_e32 v65, v103, v65
	v_add_f32_e32 v65, v104, v65
	v_add_f32_e32 v65, v105, v65
	v_cvt_pk_bf16_f32 v174, v100, v101
	v_cvt_pk_bf16_f32 v175, v102, v103
	s_waitcnt lgkmcnt(10)
	v_mfma_f32_32x32x16_bf16 v[112:127], v[200:203], v[156:159], v[230:245]
	ds_read_b64_tr_b16 v[74:75], v209 offset:25600
	ds_read_b64_tr_b16 v[76:77], v209 offset:26112
	v_add_f32_e32 v65, v106, v65
	v_add_f32_e32 v65, v107, v65
	v_add_f32_e32 v65, v108, v65
	v_add_f32_e32 v65, v109, v65
	v_cvt_pk_bf16_f32 v168, v104, v105
	v_cvt_pk_bf16_f32 v169, v106, v107
	s_waitcnt lgkmcnt(11)
	v_mfma_f32_32x32x16_bf16 v[128:143], v[196:199], v[152:155], v[128:143]
	ds_read_b64_tr_b16 v[70:71], v209 offset:29696
	ds_read_b64_tr_b16 v[72:73], v209 offset:30208
	v_add_f32_e32 v65, v110, v65
	v_add_f32_e32 v65, v111, v65
	v_add_f32_e32 v65, v80, v65
	v_add_f32_e32 v65, v81, v65
	v_cvt_pk_bf16_f32 v170, v108, v109
	v_cvt_pk_bf16_f32 v171, v110, v111
	s_waitcnt lgkmcnt(12)
	v_mfma_f32_32x32x16_bf16 v[112:127], v[192:195], v[152:155], v[112:127]
	ds_read_b64_tr_b16 v[66:67], v209 offset:26624
	ds_read_b64_tr_b16 v[68:69], v209 offset:27136
	v_add_f32_e32 v65, v82, v65
	v_add_f32_e32 v65, v83, v65
	v_add_f32_e32 v65, v84, v65
	v_add_f32_e32 v65, v85, v65
	v_cvt_pk_bf16_f32 v164, v80, v81
	v_cvt_pk_bf16_f32 v165, v82, v83
	s_waitcnt lgkmcnt(13)
	v_mfma_f32_32x32x16_bf16 v[128:143], v[188:191], v[148:151], v[128:143]
	ds_read_b64_tr_b16 v[100:101], v209 offset:30720
	ds_read_b64_tr_b16 v[102:103], v209 offset:31232
	v_add_f32_e32 v65, v86, v65
	v_add_f32_e32 v65, v87, v65
	v_add_f32_e32 v65, v88, v65
	v_add_f32_e32 v65, v89, v65
	v_cvt_pk_bf16_f32 v166, v84, v85
	v_cvt_pk_bf16_f32 v167, v86, v87
	s_waitcnt lgkmcnt(14)
	v_mfma_f32_32x32x16_bf16 v[112:127], v[184:187], v[148:151], v[112:127]
	ds_read_b64_tr_b16 v[96:97], v209 offset:27648
	ds_read_b64_tr_b16 v[98:99], v209 offset:28160
	v_add_f32_e32 v65, v90, v65
	v_add_f32_e32 v65, v91, v65
	v_add_f32_e32 v65, v92, v65
	v_add_f32_e32 v65, v93, v65
	v_cvt_pk_bf16_f32 v160, v88, v89
	v_cvt_pk_bf16_f32 v161, v90, v91
	s_waitcnt lgkmcnt(14)
	v_mfma_f32_32x32x16_bf16 v[128:143], v[180:183], v[144:147], v[128:143]
	ds_read_b64_tr_b16 v[86:87], v209 offset:31744
	ds_read_b64_tr_b16 v[88:89], v209 offset:32256
	v_add_f32_e32 v65, v94, v65
	v_add_f32_e32 v65, v95, v65
	v_add_f32_e32 v65, 0, v65
	v_cvt_pk_bf16_f32 v162, v92, v93
	v_cvt_pk_bf16_f32 v163, v94, v95
	v_mfma_f32_32x32x16_bf16 v[112:127], v[176:179], v[144:147], v[112:127]
	v_lshl_add_u64 v[190:191], v[212:213], 0, s[48:49]
	v_lshl_add_u64 v[78:79], v[190:191], 0, s[10:11]
	s_add_i32 s5, s42, s3
	s_mov_b32 s6, m0
	s_mov_b32 m0, s5
	s_nop 0
	global_load_lds_dwordx4 v[78:79], off
	s_mov_b32 m0, s6
	v_lshl_add_u64 v[188:189], v[210:211], 0, s[48:49]
	v_lshl_add_u64 v[78:79], v[188:189], 0, s[12:13]
	s_add_i32 s5, s36, s97
	s_mov_b32 s6, m0
	s_mov_b32 m0, s5
	s_nop 0
	global_load_lds_dwordx4 v[78:79], off
	s_mov_b32 m0, s6
	v_lshl_add_u64 v[78:79], v[188:189], 0, s[14:15]
	s_add_i32 s5, s36, s96
	s_mov_b32 s6, m0
	s_mov_b32 m0, s5
	s_nop 0
	global_load_lds_dwordx4 v[78:79], off
	s_mov_b32 m0, s6
	s_waitcnt lgkmcnt(14)
	v_mfma_f32_32x32x16_bf16 v[32:47], v[172:175], v[216:219], v[32:47]
	v_exp_f32_e32 v128, v128
	v_exp_f32_e32 v129, v129
	ds_read_b64_tr_b16 v[90:91], v209 offset:49152
	ds_read_b64_tr_b16 v[92:93], v209 offset:49664
	s_waitcnt lgkmcnt(14)
	v_mfma_f32_32x32x16_bf16 v[48:63], v[172:175], v[204:207], v[48:63]
	v_exp_f32_e32 v130, v130
	v_exp_f32_e32 v131, v131
	ds_read_b64_tr_b16 v[104:105], v209 offset:53248
	ds_read_b64_tr_b16 v[106:107], v209 offset:53760
	v_add_u32_e32 v94, s37, v250
	ds_read_b128 v[82:85], v94
	ds_read_b128 v[78:81], v94 offset:512
	s_waitcnt lgkmcnt(14)
	v_mfma_f32_32x32x16_bf16 v[32:47], v[168:171], v[74:77], v[32:47]
	v_exp_f32_e32 v132, v132
	v_exp_f32_e32 v133, v133
	ds_read_b64_tr_b16 v[108:109], v209 offset:50176
	ds_read_b64_tr_b16 v[110:111], v209 offset:50688
	ds_read_b128 v[184:187], v94 offset:2048
	ds_read_b128 v[176:179], v94 offset:2560
	v_mfma_f32_32x32x16_bf16 v[48:63], v[168:171], v[70:73], v[48:63]
	v_exp_f32_e32 v134, v134
	v_exp_f32_e32 v135, v135
	ds_read_b64_tr_b16 v[192:193], v209 offset:54272
	ds_read_b64_tr_b16 v[194:195], v209 offset:54784
	ds_read_b128 v[180:183], v94 offset:4096
	ds_read_b128 v[70:73], v94 offset:4608
	s_waitcnt lgkmcnt(14)
	v_mfma_f32_32x32x16_bf16 v[32:47], v[164:167], v[66:69], v[32:47]
	v_exp_f32_e32 v136, v136
	v_exp_f32_e32 v137, v137
	ds_read_b64_tr_b16 v[196:197], v209 offset:51200
	ds_read_b64_tr_b16 v[198:199], v209 offset:51712
	ds_read_b128 v[74:77], v94 offset:6144
	ds_read_b128 v[66:69], v94 offset:6656
	v_mfma_f32_32x32x16_bf16 v[48:63], v[164:167], v[100:103], v[48:63]
	v_exp_f32_e32 v138, v138
	v_exp_f32_e32 v139, v139
	ds_read_b64_tr_b16 v[100:101], v209 offset:55296
	ds_read_b64_tr_b16 v[102:103], v209 offset:55808
	v_mfma_f32_32x32x16_bf16 v[32:47], v[160:163], v[96:99], v[32:47]
	v_exp_f32_e32 v140, v140
	v_exp_f32_e32 v141, v141
	ds_read_b64_tr_b16 v[94:95], v209 offset:52224
	ds_read_b64_tr_b16 v[96:97], v209 offset:52736
	v_mfma_f32_32x32x16_bf16 v[48:63], v[160:163], v[86:89], v[48:63]
	v_exp_f32_e32 v142, v142
	v_exp_f32_e32 v143, v143
	ds_read_b64_tr_b16 v[86:87], v209 offset:56320
	ds_read_b64_tr_b16 v[88:89], v209 offset:56832
	s_waitcnt lgkmcnt(14)
	v_mfma_f32_32x32x16_bf16 v[0:15], v[172:175], v[90:93], v[0:15]
	v_exp_f32_e32 v112, v112
	v_exp_f32_e32 v113, v113
	v_mfma_f32_32x32x16_bf16 v[16:31], v[172:175], v[104:107], v[16:31]
	v_exp_f32_e32 v114, v114
	v_exp_f32_e32 v115, v115
	v_mfma_f32_32x32x16_bf16 v[0:15], v[168:171], v[108:111], v[0:15]
	v_exp_f32_e32 v116, v116
	v_exp_f32_e32 v117, v117
	s_waitcnt lgkmcnt(12)
	v_mfma_f32_32x32x16_bf16 v[16:31], v[168:171], v[192:195], v[16:31]
	v_exp_f32_e32 v118, v118
	v_exp_f32_e32 v119, v119
	s_waitcnt lgkmcnt(8)
	v_mfma_f32_32x32x16_bf16 v[0:15], v[164:167], v[196:199], v[0:15]
	v_exp_f32_e32 v120, v120
	v_exp_f32_e32 v121, v121
	s_waitcnt lgkmcnt(4)
	v_mfma_f32_32x32x16_bf16 v[16:31], v[164:167], v[100:103], v[16:31]
	v_exp_f32_e32 v122, v122
	v_exp_f32_e32 v123, v123
	s_waitcnt lgkmcnt(2)
	v_mfma_f32_32x32x16_bf16 v[0:15], v[160:163], v[94:97], v[0:15]
	v_exp_f32_e32 v124, v124
	v_exp_f32_e32 v125, v125
	s_waitcnt lgkmcnt(0)
	v_mfma_f32_32x32x16_bf16 v[16:31], v[160:163], v[86:89], v[16:31]
	v_exp_f32_e32 v126, v126
	v_exp_f32_e32 v127, v127
	s_waitcnt vmcnt(3) lgkmcnt(0)
	s_barrier
	s_add_i32 s5, s36, 0x2000
	s_cmpk_lg_i32 s36, 0x4000
	s_cselect_b32 s42, s5, 0
	v_add_u32_e32 v209, s1, v252
	ds_read_b64_tr_b16 v[192:193], v209 offset:24576
	ds_read_b64_tr_b16 v[194:195], v209 offset:25088
	v_mfma_f32_32x32x16_bf16 v[96:111], v[82:85], v[156:159], v[230:245]
	v_add_f32_e32 v86, v128, v129
	v_add_f32_e32 v86, v130, v86
	v_add_f32_e32 v86, v131, v86
	v_add_f32_e32 v86, v132, v86
	v_add_f32_e32 v86, v133, v86
	v_cvt_pk_bf16_f32 v172, v128, v129
	v_cvt_pk_bf16_f32 v173, v130, v131
	ds_read_b64_tr_b16 v[196:197], v209 offset:28672
	ds_read_b64_tr_b16 v[198:199], v209 offset:29184
	v_add_f32_e32 v82, v134, v86
	v_add_f32_e32 v82, v135, v82
	v_add_f32_e32 v82, v136, v82
	v_add_f32_e32 v128, v137, v82
	v_mfma_f32_32x32x16_bf16 v[80:95], v[78:81], v[156:159], v[230:245]
	v_cvt_pk_bf16_f32 v174, v132, v133
	v_cvt_pk_bf16_f32 v175, v134, v135
	ds_read_b64_tr_b16 v[216:217], v209 offset:25600
	ds_read_b64_tr_b16 v[218:219], v209 offset:26112
	v_mfma_f32_32x32x16_bf16 v[96:111], v[184:187], v[152:155], v[96:111]
	v_add_f32_e32 v78, v138, v128
	v_add_f32_e32 v78, v139, v78
	v_add_f32_e32 v78, v140, v78
	v_add_f32_e32 v78, v141, v78
	v_cvt_pk_bf16_f32 v168, v136, v137
	v_cvt_pk_bf16_f32 v169, v138, v139
	ds_read_b64_tr_b16 v[136:137], v209 offset:29696
	ds_read_b64_tr_b16 v[138:139], v209 offset:30208
	v_mfma_f32_32x32x16_bf16 v[80:95], v[176:179], v[152:155], v[80:95]
	v_add_f32_e32 v78, v142, v78
	v_add_f32_e32 v78, v143, v78
	v_add_f32_e32 v78, v112, v78
	v_add_f32_e32 v78, v113, v78
	v_cvt_pk_bf16_f32 v170, v140, v141
	v_cvt_pk_bf16_f32 v171, v142, v143
	ds_read_b64_tr_b16 v[132:133], v209 offset:26624
	ds_read_b64_tr_b16 v[134:135], v209 offset:27136
	v_mfma_f32_32x32x16_bf16 v[96:111], v[180:183], v[148:151], v[96:111]
	v_add_f32_e32 v78, v114, v78
	v_add_f32_e32 v78, v115, v78
	v_add_f32_e32 v78, v116, v78
	v_add_f32_e32 v78, v117, v78
	v_cvt_pk_bf16_f32 v164, v112, v113
	v_cvt_pk_bf16_f32 v165, v114, v115
	ds_read_b64_tr_b16 v[128:129], v209 offset:30720
	ds_read_b64_tr_b16 v[130:131], v209 offset:31232
	v_mfma_f32_32x32x16_bf16 v[80:95], v[70:73], v[148:151], v[80:95]
	v_add_f32_e32 v78, v118, v78
	v_add_f32_e32 v78, v119, v78
	v_add_f32_e32 v78, v120, v78
	v_add_f32_e32 v78, v121, v78
	v_cvt_pk_bf16_f32 v166, v116, v117
	v_cvt_pk_bf16_f32 v167, v118, v119
	ds_read_b64_tr_b16 v[112:113], v209 offset:27648
	ds_read_b64_tr_b16 v[114:115], v209 offset:28160
	v_mfma_f32_32x32x16_bf16 v[96:111], v[74:77], v[144:147], v[96:111]
	v_add_f32_e32 v70, v122, v78
	v_add_f32_e32 v70, v123, v70
	v_add_f32_e32 v70, v124, v70
	v_add_f32_e32 v78, v125, v70
	v_cvt_pk_bf16_f32 v160, v120, v121
	v_cvt_pk_bf16_f32 v161, v122, v123
	ds_read_b64_tr_b16 v[70:71], v209 offset:31744
	ds_read_b64_tr_b16 v[72:73], v209 offset:32256
	v_mfma_f32_32x32x16_bf16 v[80:95], v[66:69], v[144:147], v[80:95]
	v_add_f32_e32 v74, v126, v78
	v_add_f32_e32 v74, v127, v74
	v_add_f32_e32 v74, 0, v74
	v_cvt_pk_bf16_f32 v162, v124, v125
	v_cvt_pk_bf16_f32 v163, v126, v127
	v_lshl_add_u64 v[66:67], v[190:191], 0, s[16:17]
	s_add_i32 s1, s36, s3
	s_mov_b32 s5, m0
	s_mov_b32 m0, s1
	s_nop 0
	global_load_lds_dwordx4 v[66:67], off
	s_mov_b32 m0, s5
	v_lshl_add_u64 v[66:67], v[188:189], 0, s[18:19]
	s_add_i32 s1, s42, s97
	s_mov_b32 s5, m0
	s_mov_b32 m0, s1
	s_nop 0
	global_load_lds_dwordx4 v[66:67], off
	s_mov_b32 m0, s5
	v_lshl_add_u64 v[66:67], v[188:189], 0, s[20:21]
	s_add_i32 s1, s42, s96
	s_mov_b32 s5, m0
	s_mov_b32 m0, s1
	s_nop 0
	global_load_lds_dwordx4 v[66:67], off
	s_mov_b32 m0, s5
	s_waitcnt lgkmcnt(14)
	v_mfma_f32_32x32x16_bf16 v[32:47], v[172:175], v[192:195], v[32:47]
	v_exp_f32_e32 v96, v96
	v_exp_f32_e32 v97, v97
	ds_read_b64_tr_b16 v[66:67], v209 offset:49152
	ds_read_b64_tr_b16 v[68:69], v209 offset:49664
	s_waitcnt lgkmcnt(14)
	v_mfma_f32_32x32x16_bf16 v[48:63], v[172:175], v[196:199], v[48:63]
	v_exp_f32_e32 v98, v98
	v_exp_f32_e32 v99, v99
	ds_read_b64_tr_b16 v[76:77], v209 offset:53248
	ds_read_b64_tr_b16 v[78:79], v209 offset:53760
	v_add_u32_e32 v75, s42, v250
	ds_read_b128 v[204:207], v75
	ds_read_b128 v[200:203], v75 offset:512
	s_waitcnt lgkmcnt(14)
	v_mfma_f32_32x32x16_bf16 v[32:47], v[168:171], v[216:219], v[32:47]
	v_exp_f32_e32 v100, v100
	v_exp_f32_e32 v101, v101
	ds_read_b64_tr_b16 v[116:117], v209 offset:50176
	ds_read_b64_tr_b16 v[118:119], v209 offset:50688
	ds_read_b128 v[196:199], v75 offset:2048
	ds_read_b128 v[192:195], v75 offset:2560
	v_mfma_f32_32x32x16_bf16 v[48:63], v[168:171], v[136:139], v[48:63]
	v_exp_f32_e32 v102, v102
	v_exp_f32_e32 v103, v103
	ds_read_b64_tr_b16 v[120:121], v209 offset:54272
	ds_read_b64_tr_b16 v[122:123], v209 offset:54784
	ds_read_b128 v[188:191], v75 offset:4096
	ds_read_b128 v[184:187], v75 offset:4608
	s_waitcnt lgkmcnt(14)
	v_mfma_f32_32x32x16_bf16 v[32:47], v[164:167], v[132:135], v[32:47]
	v_exp_f32_e32 v104, v104
	v_exp_f32_e32 v105, v105
	ds_read_b64_tr_b16 v[124:125], v209 offset:51200
	ds_read_b64_tr_b16 v[126:127], v209 offset:51712
	ds_read_b128 v[180:183], v75 offset:6144
	ds_read_b128 v[176:179], v75 offset:6656
	v_mfma_f32_32x32x16_bf16 v[48:63], v[164:167], v[128:131], v[48:63]
	v_exp_f32_e32 v106, v106
	v_exp_f32_e32 v107, v107
	ds_read_b64_tr_b16 v[128:129], v209 offset:55296
	ds_read_b64_tr_b16 v[130:131], v209 offset:55808
	v_mfma_f32_32x32x16_bf16 v[32:47], v[160:163], v[112:115], v[32:47]
	v_exp_f32_e32 v108, v108
	v_exp_f32_e32 v109, v109
	ds_read_b64_tr_b16 v[112:113], v209 offset:52224
	ds_read_b64_tr_b16 v[114:115], v209 offset:52736
	v_mfma_f32_32x32x16_bf16 v[48:63], v[160:163], v[70:73], v[48:63]
	v_exp_f32_e32 v110, v110
	v_exp_f32_e32 v111, v111
	ds_read_b64_tr_b16 v[70:71], v209 offset:56320
	ds_read_b64_tr_b16 v[72:73], v209 offset:56832
	s_waitcnt lgkmcnt(14)
	v_mfma_f32_32x32x16_bf16 v[0:15], v[172:175], v[66:69], v[0:15]
	v_exp_f32_e32 v80, v80
	v_exp_f32_e32 v81, v81
	v_mfma_f32_32x32x16_bf16 v[16:31], v[172:175], v[76:79], v[16:31]
	v_exp_f32_e32 v82, v82
	v_exp_f32_e32 v83, v83
	v_mfma_f32_32x32x16_bf16 v[0:15], v[168:171], v[116:119], v[0:15]
	v_exp_f32_e32 v84, v84
	v_exp_f32_e32 v85, v85
	s_waitcnt lgkmcnt(12)
	v_mfma_f32_32x32x16_bf16 v[16:31], v[168:171], v[120:123], v[16:31]
	v_exp_f32_e32 v86, v86
	v_exp_f32_e32 v87, v87
	s_waitcnt lgkmcnt(8)
	v_mfma_f32_32x32x16_bf16 v[0:15], v[164:167], v[124:127], v[0:15]
	v_exp_f32_e32 v88, v88
	v_exp_f32_e32 v89, v89
	s_waitcnt lgkmcnt(4)
	v_mfma_f32_32x32x16_bf16 v[16:31], v[164:167], v[128:131], v[16:31]
	v_exp_f32_e32 v90, v90
	v_exp_f32_e32 v91, v91
	s_waitcnt lgkmcnt(2)
	v_mfma_f32_32x32x16_bf16 v[0:15], v[160:163], v[112:115], v[0:15]
	v_exp_f32_e32 v92, v92
	v_exp_f32_e32 v93, v93
	s_waitcnt lgkmcnt(0)
	v_mfma_f32_32x32x16_bf16 v[16:31], v[160:163], v[70:73], v[16:31]
	v_exp_f32_e32 v94, v94
	v_exp_f32_e32 v95, v95
	s_add_i32 s1, s42, 0x2000
	s_waitcnt vmcnt(3) lgkmcnt(0)
	s_barrier
; #define WAIT_BAR(N) asm volatile("s_waitcnt vmcnt(" #N ") lgkmcnt(0)\n\ts_barrier":::"memory")
;   #define RESC() do{ if(resc){ asm volatile("s_waitcnt lgkmcnt(0)":::"memory"); \
;       _Pragma("unroll") for(int d_=0;d_<2;++d_) _Pragma("unroll") for(int r=0;r<16;++r){const float f_=wsf[crow(r,hi)];o[d_][r]*=f_;o2[d_][r]*=f_;} } }while(0)
;   #define ROT() do{sl_prev=sl_cur;sl_cur=sl_next;sl_next=(sl_next==(NSLOT-1)*SLOTB)?0:sl_next+SLOTB;}while(0)
; template<int THRL> __device__ __forceinline__ void attn_unit(int b,int h,int qb,unsigned char*wsb,char*shm,float kmax,const int CMB,float lam){
;     ...
;   for(;t+5<NT;t+=2){
;     STEP(pB0,pB1,pA0,pA1,t,true,true,true);     WAIT_BAR(3); RESC(); ROT();
;     STEP(pA0,pA1,pB0,pB1,t+1,true,true,true);   WAIT_BAR(3); RESC(); ROT();
;   }
	s_cmpk_lg_i32 s42, 0x4000
	v_add_f32_e32 v64, v64, v65
	s_mov_b32 s5, s36
	s_cselect_b32 s36, s1, 0
	s_add_i32 s33, s33, 2
	v_lshl_add_u64 v[210:211], v[210:211], 0, s[22:23]
	v_lshl_add_u64 v[212:213], v[212:213], 0, s[22:23]
	s_cmp_ge_u32 s33, s89
	v_add_f32_e32 v64, v64, v74
	s_cbranch_scc0 .LBB0_311
	ds_read_b32 v230, v246
	ds_read_b32 v231, v246 offset:2048
	ds_read_b32 v232, v246 offset:4096
	ds_read_b32 v233, v246 offset:6144
	ds_read_b32 v234, v246 offset:8192
	ds_read_b32 v235, v246 offset:10240
	ds_read_b32 v236, v246 offset:12288
	ds_read_b32 v237, v246 offset:14336
	ds_read_b32 v238, v246 offset:16384
	ds_read_b32 v239, v246 offset:18432
	ds_read_b32 v240, v246 offset:20480
	ds_read_b32 v241, v246 offset:22528
	ds_read_b32 v242, v246 offset:24576
	ds_read_b32 v243, v246 offset:26624
	ds_read_b32 v244, v246 offset:28672
	ds_read_b32 v245, v246 offset:30720
	ds_read_b32 v246, v246 offset:32768
	s_waitcnt lgkmcnt(0)
	s_nop 0
	s_nop 0
	s_nop 0
	s_nop 0
	s_nop 0
	s_nop 0
	s_nop 0
	s_nop 0
	s_add_i32 s6, s4, -3
	s_branch .LBB0_314
